# inproj1 rope section: dead address arithmetic (216 VALU ops that only fed the replaced loads) removed from both hand-scheduled copies
# baseline (speedup 1.0000x reference)
.LBB0_437:
	s_andn2_b64 vcc, exec, s[4:5]
	s_mov_b64 s[4:5], 0x1000
	s_cbranch_vccnz .LBB0_443
	s_cmp_lg_u32 s65, 0
	s_cbranch_scc0 .LBB0_447
	s_lshl_b64 s[58:59], s[0:1], 13
	s_cmp_eq_u32 s65, 1
	s_cselect_b64 s[56:57], -1, 0
	s_and_b64 s[0:1], s[56:57], exec
	s_cselect_b32 s1, s43, s45
	s_cselect_b32 s0, s42, s44
	v_mov_b32_e32 v120, v18
	v_mov_b32_e32 v121, v22
	v_mul_f32_e32 v122, v120, v120
	v_mul_f32_e32 v123, v121, v121
	global_load_dword v143, v192, s[0:1]
	global_load_dword v141, v192, s[0:1] offset:64
	global_load_dword v125, v192, s[0:1] offset:128
	global_load_dword v121, v192, s[0:1] offset:192
	global_load_dword v142, v192, s[0:1] offset:256
	global_load_dword v140, v192, s[0:1] offset:320
	v_and_b32_e32 v77, 64, v201
	v_xor_b32_e32 v76, 1, v201
	v_add_u32_e32 v77, 64, v77
	v_cmp_lt_i32_e32 vcc, v76, v77
	v_mov_b32_e32 v82, v41
	v_mov_b32_e32 v83, v45
	v_cndmask_b32_e32 v76, v201, v76, vcc
	v_lshlrev_b32_e32 v146, 2, v76
	v_xor_b32_e32 v76, 2, v201
	v_cmp_lt_i32_e32 vcc, v76, v77
	v_mul_f32_e32 v82, v82, v82
	v_mul_f32_e32 v83, v83, v83
	v_mul_f32_e32 v86, v36, v36
	v_mul_f32_e32 v87, v37, v37
	v_cndmask_b32_e32 v76, v201, v76, vcc
	v_lshlrev_b32_e32 v147, 2, v76
	v_xor_b32_e32 v76, 4, v201
	v_cmp_lt_i32_e32 vcc, v76, v77
	v_mov_b32_e32 v78, v48
	v_mov_b32_e32 v79, v52
	v_cndmask_b32_e32 v76, v201, v76, vcc
	v_lshlrev_b32_e32 v148, 2, v76
	v_xor_b32_e32 v76, 8, v201
	v_cmp_lt_i32_e32 vcc, v76, v77
	v_mov_b32_e32 v77, v44
	v_fma_f32 v86, v32, v32, v86
	v_fma_f32 v87, v33, v33, v87
	v_cndmask_b32_e32 v76, v201, v76, vcc
	v_lshlrev_b32_e32 v149, 2, v76
	v_mov_b32_e32 v76, v40
	v_mul_f32_e32 v76, v76, v76
	v_mul_f32_e32 v77, v77, v77
	v_mov_b32_e32 v88, v49
	v_mov_b32_e32 v89, v53
	v_mov_b32_e32 v126, v82
	v_mov_b32_e32 v127, v76
	v_mul_f32_e32 v78, v78, v78
	v_mul_f32_e32 v79, v79, v79
	v_mul_f32_e32 v88, v88, v88
	v_mul_f32_e32 v89, v89, v89
	v_pk_add_f32 v[86:87], v[86:87], v[126:127] op_sel:[1,0] op_sel_hi:[0,1]
	v_mov_b32_e32 v76, v83
	v_mov_b32_e32 v80, v56
	v_mov_b32_e32 v81, v60
	v_mov_b32_e32 v90, v57
	v_mov_b32_e32 v91, v61
	v_add_f32_e32 v76, v86, v76
	v_add_f32_e32 v77, v87, v77
	v_mov_b32_e32 v82, v88
	v_mov_b32_e32 v83, v78
	v_mul_f32_e32 v80, v80, v80
	v_mul_f32_e32 v81, v81, v81
	v_mul_f32_e32 v90, v90, v90
	v_mul_f32_e32 v91, v91, v91
	v_add_f32_e32 v76, v76, v82
	v_add_f32_e32 v77, v77, v83
	v_mov_b32_e32 v78, v89
	v_add_f32_e32 v76, v76, v78
	v_add_f32_e32 v77, v77, v79
	v_mov_b32_e32 v78, v90
	v_mov_b32_e32 v79, v80
	v_add_f32_e32 v76, v76, v78
	v_add_f32_e32 v77, v77, v79
	v_mov_b32_e32 v80, v91
	v_add_f32_e32 v76, v76, v80
	v_add_f32_e32 v77, v77, v81
	s_nop 1
	v_mov_b32_dpp v79, v77 quad_perm:[1,0,3,2] row_mask:0xf bank_mask:0xf
	v_mov_b32_dpp v78, v76 quad_perm:[1,0,3,2] row_mask:0xf bank_mask:0xf
	global_load_dword v124, v192, s[0:1] offset:384
	global_load_dword v120, v192, s[0:1] offset:448
	v_mov_b32_e32 v88, v3
	v_mov_b32_e32 v89, v11
	s_waitcnt lgkmcnt(0)
	v_add_f32_e32 v76, v76, v78
	v_add_f32_e32 v77, v77, v79
	s_nop 1
	v_mov_b32_dpp v79, v77 quad_perm:[2,3,0,1] row_mask:0xf bank_mask:0xf
	v_mov_b32_dpp v78, v76 quad_perm:[2,3,0,1] row_mask:0xf bank_mask:0xf
	v_mov_b32_e32 v92, v42
	v_mov_b32_e32 v93, v46
	v_mov_b32_e32 v98, v43
	v_mov_b32_e32 v99, v47
	s_waitcnt lgkmcnt(0)
	v_add_f32_e32 v76, v76, v78
	v_add_f32_e32 v77, v77, v79
	s_nop 1
	v_mov_b32_dpp v79, v77 row_half_mirror row_mask:0xf bank_mask:0xf
	v_mov_b32_dpp v78, v76 row_half_mirror row_mask:0xf bank_mask:0xf
	v_mul_f32_e32 v90, v88, v88
	v_mul_f32_e32 v91, v89, v89
	v_mov_b32_e32 v88, v27
	v_mov_b32_e32 v89, v31
	v_mul_f32_e32 v84, v38, v38
	v_mul_f32_e32 v85, v39, v39
	s_waitcnt lgkmcnt(0)
	v_add_f32_e32 v76, v76, v78
	v_add_f32_e32 v77, v77, v79
	s_nop 1
	v_mov_b32_dpp v79, v77 row_mirror row_mask:0xf bank_mask:0xf
	v_mov_b32_dpp v78, v76 row_mirror row_mask:0xf bank_mask:0xf
	v_mul_f32_e32 v92, v92, v92
	v_mul_f32_e32 v93, v93, v93
	v_mul_f32_e32 v98, v98, v98
	v_mul_f32_e32 v99, v99, v99
	v_fma_f32 v84, v34, v34, v84
	v_fma_f32 v85, v35, v35, v85
	v_mov_b32_e32 v94, v50
	s_waitcnt lgkmcnt(0)
	v_add_f32_e32 v76, v76, v78
	v_add_f32_e32 v77, v77, v79
	v_mov_b64_e32 v[78:79], s[52:53]
	v_fma_f32 v76, v76, s46, v78
	v_fma_f32 v77, v77, s46, v78
	v_mov_b32_e32 v95, v54
	v_mul_f32_e32 v126, 0x4b800000, v77
	v_cmp_gt_f32_e32 vcc, s60, v77
	v_cmp_gt_f32_e64 s[0:1], s60, v76
	v_mov_b32_e32 v100, v51
	v_cndmask_b32_e32 v77, v77, v126, vcc
	v_rsq_f32_e32 v126, v77
	v_mul_f32_e32 v77, 0x4b800000, v76
	v_cndmask_b32_e64 v76, v76, v77, s[0:1]
	v_rsq_f32_e32 v127, v76
	v_mul_f32_e32 v76, v88, v88
	v_mul_f32_e32 v77, v89, v89
	v_mul_f32_e32 v88, 0x45800000, v126
	v_mov_b32_e32 v101, v55
	v_cndmask_b32_e32 v126, v126, v88, vcc
	v_mov_b32_e32 v88, v98
	v_mov_b32_e32 v89, v92
	v_mul_f32_e32 v94, v94, v94
	v_mul_f32_e32 v95, v95, v95
	v_mul_f32_e32 v100, v100, v100
	v_mul_f32_e32 v101, v101, v101
	v_pk_add_f32 v[84:85], v[84:85], v[88:89] op_sel:[1,0] op_sel_hi:[0,1]
	v_mov_b32_e32 v92, v99
	v_mov_b32_e32 v96, v58
	v_mov_b32_e32 v97, v62
	v_mov_b32_e32 v102, v59
	v_mov_b32_e32 v103, v63
	v_add_f32_e32 v84, v84, v92
	v_add_f32_e32 v85, v85, v93
	v_mov_b32_e32 v88, v100
	v_mov_b32_e32 v89, v94
	v_mul_f32_e32 v96, v96, v96
	v_mul_f32_e32 v97, v97, v97
	v_mul_f32_e32 v102, v102, v102
	v_mul_f32_e32 v103, v103, v103
	v_add_f32_e32 v84, v84, v88
	v_add_f32_e32 v85, v85, v89
	v_mov_b32_e32 v94, v101
	v_add_f32_e32 v84, v84, v94
	v_add_f32_e32 v85, v85, v95
	v_mov_b32_e32 v88, v102
	v_mov_b32_e32 v89, v96
	v_add_f32_e32 v84, v84, v88
	v_add_f32_e32 v85, v85, v89
	v_mov_b32_e32 v96, v103
	v_add_f32_e32 v84, v84, v96
	v_add_f32_e32 v85, v85, v97
	s_nop 1
	v_mov_b32_dpp v89, v85 quad_perm:[1,0,3,2] row_mask:0xf bank_mask:0xf
	v_mov_b32_dpp v88, v84 quad_perm:[1,0,3,2] row_mask:0xf bank_mask:0xf
	v_mul_f32_e32 v144, 0x45800000, v127
	v_mov_b32_e32 v104, v16
	v_mov_b32_e32 v105, v20
	v_mov_b32_e32 v110, v17
	s_waitcnt lgkmcnt(0)
	v_add_f32_e32 v84, v84, v88
	v_add_f32_e32 v85, v85, v89
	s_nop 1
	v_mov_b32_dpp v89, v85 quad_perm:[2,3,0,1] row_mask:0xf bank_mask:0xf
	v_mov_b32_dpp v88, v84 quad_perm:[2,3,0,1] row_mask:0xf bank_mask:0xf
	v_mov_b32_e32 v111, v21
	v_cndmask_b32_e64 v96, v127, v144, s[0:1]
	v_mul_f32_e32 v104, v104, v104
	v_mul_f32_e32 v105, v105, v105
	v_mul_f32_e32 v110, v110, v110
	v_mul_f32_e32 v111, v111, v111
	v_mul_f32_e32 v114, v12, v12
	v_mul_f32_e32 v115, v13, v13
	s_waitcnt vmcnt(0)
	v_mul_f32_e32 v92, v96, v143
	v_mov_b32_e32 v106, v0
	v_mov_b32_e32 v107, v8
	v_fma_f32 v114, v4, v4, v114
	v_fma_f32 v115, v5, v5, v115
	v_mov_b32_e32 v116, v1
	v_mov_b32_e32 v117, v9
	v_mul_f32_e32 v127, v33, v92
	s_waitcnt lgkmcnt(0)
	v_add_f32_e32 v84, v84, v88
	v_add_f32_e32 v85, v85, v89
	v_mov_b32_e32 v92, v110
	v_mov_b32_e32 v93, v104
	v_mul_f32_e32 v106, v106, v106
	v_mul_f32_e32 v107, v107, v107
	v_mul_f32_e32 v116, v116, v116
	v_mul_f32_e32 v117, v117, v117
	v_mov_b32_dpp v89, v85 row_half_mirror row_mask:0xf bank_mask:0xf
	v_mov_b32_dpp v88, v84 row_half_mirror row_mask:0xf bank_mask:0xf
	v_add_f32_e32 v92, v115, v92
	v_add_f32_e32 v93, v114, v93
	v_mov_b32_e32 v104, v111
	v_mov_b32_e32 v108, v24
	v_mov_b32_e32 v109, v28
	v_mov_b32_e32 v118, v25
	v_mov_b32_e32 v119, v29
	v_add_f32_e32 v92, v92, v104
	v_add_f32_e32 v93, v93, v105
	v_mov_b32_e32 v94, v116
	v_mov_b32_e32 v95, v106
	v_mul_f32_e32 v108, v108, v108
	v_mul_f32_e32 v109, v109, v109
	v_mul_f32_e32 v118, v118, v118
	v_mul_f32_e32 v119, v119, v119
	v_add_f32_e32 v92, v92, v94
	v_add_f32_e32 v93, v93, v95
	v_mov_b32_e32 v106, v117
	v_add_f32_e32 v92, v92, v106
	v_add_f32_e32 v93, v93, v107
	v_mov_b32_e32 v94, v118
	v_mov_b32_e32 v95, v108
	v_add_f32_e32 v92, v92, v94
	v_add_f32_e32 v93, v93, v95
	v_mov_b32_e32 v108, v119
	s_waitcnt lgkmcnt(0)
	v_add_f32_e32 v84, v84, v88
	v_add_f32_e32 v85, v85, v89
	v_add_f32_e32 v92, v92, v108
	v_add_f32_e32 v93, v93, v109
	v_mov_b32_dpp v89, v85 row_mirror row_mask:0xf bank_mask:0xf
	v_mov_b32_dpp v88, v84 row_mirror row_mask:0xf bank_mask:0xf
	v_mov_b32_dpp v95, v93 quad_perm:[1,0,3,2] row_mask:0xf bank_mask:0xf
	v_mov_b32_dpp v94, v92 quad_perm:[1,0,3,2] row_mask:0xf bank_mask:0xf
	v_mul_f32_e32 v33, v96, v141
	v_mul_f32_e32 v150, v37, v33
	s_waitcnt lgkmcnt(2)
	v_add_f32_e32 v84, v84, v88
	v_add_f32_e32 v85, v85, v89
	v_mul_f32_e32 v33, v96, v125
	s_waitcnt lgkmcnt(0)
	v_add_f32_e32 v88, v92, v94
	v_add_f32_e32 v89, v93, v95
	s_nop 1
	v_mov_b32_dpp v93, v89 quad_perm:[2,3,0,1] row_mask:0xf bank_mask:0xf
	v_mov_b32_dpp v92, v88 quad_perm:[2,3,0,1] row_mask:0xf bank_mask:0xf
	v_fma_f32 v84, v84, s46, v78
	v_fma_f32 v85, v85, s46, v78
	v_mul_f32_e32 v151, v41, v33
	v_mul_f32_e32 v37, 0x4b800000, v85
	v_cmp_gt_f32_e32 vcc, s60, v85
	s_waitcnt lgkmcnt(0)
	v_add_f32_e32 v88, v88, v92
	v_add_f32_e32 v89, v89, v93
	s_nop 1
	v_mov_b32_dpp v93, v89 row_half_mirror row_mask:0xf bank_mask:0xf
	v_mov_b32_dpp v92, v88 row_half_mirror row_mask:0xf bank_mask:0xf
	v_mul_f32_e32 v41, 0x4b800000, v84
	v_cmp_gt_f32_e64 s[0:1], s60, v84
	v_cndmask_b32_e32 v37, v85, v37, vcc
	v_mul_f32_e32 v33, v96, v121
	s_waitcnt lgkmcnt(0)
	v_add_f32_e32 v88, v88, v92
	v_add_f32_e32 v89, v89, v93
	s_nop 1
	v_mov_b32_dpp v93, v89 row_mirror row_mask:0xf bank_mask:0xf
	v_mov_b32_dpp v92, v88 row_mirror row_mask:0xf bank_mask:0xf
	v_cndmask_b32_e64 v41, v84, v41, s[0:1]
	v_mul_f32_e32 v203, v45, v33
	v_mul_f32_e32 v33, v96, v142
	v_rsq_f32_e32 v37, v37
	s_waitcnt lgkmcnt(0)
	v_add_f32_e32 v84, v88, v92
	v_add_f32_e32 v85, v89, v93
	v_mul_f32_e32 v204, v49, v33
	v_fma_f32 v84, v84, s46, v78
	v_fma_f32 v85, v85, s46, v78
	v_mul_f32_e32 v33, v96, v140
	v_mul_f32_e32 v45, 0x4b800000, v85
	v_cmp_gt_f32_e64 s[4:5], s60, v85
	v_rsq_f32_e32 v41, v41
	v_mul_f32_e32 v104, v53, v33
	v_cndmask_b32_e64 v45, v85, v45, s[4:5]
	v_mul_f32_e32 v33, v96, v124
	v_rsq_f32_e32 v45, v45
	v_mul_f32_e32 v105, v57, v33
	v_mul_f32_e32 v33, v96, v120
	v_mul_f32_e32 v106, v61, v33
	v_mul_f32_e32 v33, 0x45800000, v37
	v_cndmask_b32_e32 v92, v37, v33, vcc
	v_mul_f32_e32 v33, 0x45800000, v41
	v_cndmask_b32_e64 v88, v41, v33, s[0:1]
	v_mul_f32_e32 v33, 0x45800000, v45
	v_cndmask_b32_e64 v108, v45, v33, s[4:5]
	v_mul_f32_e32 v33, 0x4b800000, v84
	v_cmp_gt_f32_e32 vcc, s60, v84
	v_mov_b32_e32 v86, v19
	v_mov_b32_e32 v87, v23
	v_cndmask_b32_e32 v33, v84, v33, vcc
	v_lshl_add_u64 v[84:85], s[58:59], 0, v[72:73]
	v_lshlrev_b64 v[144:145], 2, v[84:85]
	s_cmp_lg_u32 s89, 0
	s_cbranch_scc1 .Lmy_rp_p2
	ds_write_b32 v129, v66 offset:45056
	ds_write_b32 v129, v67 offset:45060
	ds_write_b32 v129, v68 offset:45064
	ds_write_b32 v129, v69 offset:45068
	ds_write_b32 v129, v71 offset:49152
	ds_write_b32 v129, v74 offset:49156
	ds_write_b32 v129, v75 offset:49160
	ds_write_b32 v129, v160 offset:49164
	ds_write_b32 v129, v161 offset:53248
	ds_write_b32 v129, v162 offset:53252
	ds_write_b32 v129, v185 offset:53256
	ds_write_b32 v129, v186 offset:53260
	ds_write_b32 v129, v187 offset:57344
	ds_write_b32 v129, v207 offset:57348
	ds_write_b32 v129, v212 offset:57352
	ds_write_b32 v129, v213 offset:57356
	s_waitcnt lgkmcnt(0)
	s_add_u32 s10, s6, 0x1000
	s_addc_u32 s11, s7, 0
	s_add_u32 s12, s8, 0x1000
	s_addc_u32 s13, s9, 0
	global_load_dword v161, v144, s[6:7] offset:256
	global_load_dword v162, v144, s[8:9] offset:256
	global_load_dword v185, v144, s[6:7] offset:320
	global_load_dword v186, v144, s[8:9] offset:320
	global_load_dword v187, v144, s[6:7] offset:384
	global_load_dword v207, v144, s[8:9] offset:384
	global_load_dword v212, v144, s[6:7] offset:448
	global_load_dword v213, v144, s[8:9] offset:448
	global_load_dword v66, v144, s[6:7] offset:512
	global_load_dword v67, v144, s[8:9] offset:512
	global_load_dword v68, v144, s[6:7] offset:576
	global_load_dword v69, v144, s[8:9] offset:576
	global_load_dword v71, v144, s[6:7] offset:640
	global_load_dword v74, v144, s[8:9] offset:640
	global_load_dword v75, v144, s[6:7] offset:704
	global_load_dword v160, v144, s[8:9] offset:704
	v_lshl_add_u64 v[84:85], s[6:7], 0, v[144:145]
	v_lshl_add_u64 v[94:95], s[8:9], 0, v[144:145]
	global_load_dword v85, v[84:85], off
	s_nop 0
	global_load_dword v84, v[94:95], off
	v_or_b32_e32 v94, 64, v144
	v_mov_b32_e32 v95, v145
	v_lshl_add_u64 v[96:97], s[6:7], 0, v[94:95]
	v_lshl_add_u64 v[94:95], s[8:9], 0, v[94:95]
	global_load_dword v97, v[96:97], off
	s_nop 0
	global_load_dword v96, v[94:95], off
	v_or_b32_e32 v98, 0x80, v144
	v_mov_b32_e32 v99, v145
	v_lshl_add_u64 v[100:101], s[6:7], 0, v[98:99]
	v_lshl_add_u64 v[98:99], s[8:9], 0, v[98:99]
	global_load_dword v101, v[100:101], off
	s_nop 0
	global_load_dword v100, v[98:99], off
	v_or_b32_e32 v98, 0xc0, v144
	v_mov_b32_e32 v99, v145
	v_lshl_add_u64 v[102:103], s[6:7], 0, v[98:99]
	v_lshl_add_u64 v[98:99], s[8:9], 0, v[98:99]
	global_load_dword v103, v[102:103], off
	s_nop 0
	global_load_dword v102, v[98:99], off
	v_mul_f32_e32 v112, v14, v14
	v_mul_f32_e32 v113, v15, v15
	v_mul_f32_e32 v86, v86, v86
	v_mul_f32_e32 v87, v87, v87
	v_fma_f32 v112, v6, v6, v112
	v_fma_f32 v113, v7, v7, v113
	v_mov_b32_e32 v80, v2
	v_mov_b32_e32 v81, v10
	v_mov_b32_e32 v94, v86
	v_mov_b32_e32 v95, v122
	v_mul_f32_e32 v80, v80, v80
	v_mul_f32_e32 v81, v81, v81
	v_add_f32_e32 v94, v113, v94
	v_add_f32_e32 v95, v112, v95
	v_mov_b32_e32 v122, v87
	v_mov_b32_e32 v82, v26
	v_mov_b32_e32 v83, v30
	v_add_f32_e32 v86, v94, v122
	v_add_f32_e32 v87, v95, v123
	v_mov_b32_e32 v94, v90
	v_mov_b32_e32 v95, v80
	v_mul_f32_e32 v82, v82, v82
	v_mul_f32_e32 v83, v83, v83
	v_add_f32_e32 v86, v86, v94
	v_add_f32_e32 v87, v87, v95
	v_mov_b32_e32 v80, v91
	v_add_f32_e32 v80, v86, v80
	v_add_f32_e32 v81, v87, v81
	v_mov_b32_e32 v86, v76
	v_mov_b32_e32 v87, v82
	v_add_f32_e32 v80, v80, v86
	v_add_f32_e32 v81, v81, v87
	v_mov_b32_e32 v82, v77
	v_add_f32_e32 v76, v80, v82
	v_add_f32_e32 v77, v81, v83
	s_nop 1
	v_mov_b32_dpp v81, v77 quad_perm:[1,0,3,2] row_mask:0xf bank_mask:0xf
	v_mov_b32_dpp v80, v76 quad_perm:[1,0,3,2] row_mask:0xf bank_mask:0xf
	v_rsq_f32_e32 v33, v33
	v_mov_b32_e32 v49, v32
	v_mov_b32_e32 v53, v36
	v_mov_b32_e32 v57, v40
	s_waitcnt lgkmcnt(0)
	v_add_f32_e32 v76, v76, v80
	v_add_f32_e32 v77, v77, v81
	s_nop 1
	v_mov_b32_dpp v81, v77 quad_perm:[2,3,0,1] row_mask:0xf bank_mask:0xf
	v_mov_b32_dpp v80, v76 quad_perm:[2,3,0,1] row_mask:0xf bank_mask:0xf
	v_mul_f32_e32 v37, 0x45800000, v33
	v_cndmask_b32_e32 v33, v33, v37, vcc
	v_mul_f32_e32 v37, v33, v143
	v_mul_f32_e32 v41, v5, v37
	s_waitcnt lgkmcnt(0)
	v_add_f32_e32 v76, v76, v80
	v_add_f32_e32 v77, v77, v81
	s_nop 1
	v_mov_b32_dpp v81, v77 row_half_mirror row_mask:0xf bank_mask:0xf
	v_mov_b32_dpp v80, v76 row_half_mirror row_mask:0xf bank_mask:0xf
	v_mul_f32_e32 v5, v33, v141
	v_mul_f32_e32 v45, v13, v5
	v_mul_f32_e32 v5, v33, v125
	v_mul_f32_e32 v5, v17, v5
	s_waitcnt lgkmcnt(0)
	v_add_f32_e32 v76, v76, v80
	v_add_f32_e32 v77, v77, v81
	s_nop 1
	v_mov_b32_dpp v81, v77 row_mirror row_mask:0xf bank_mask:0xf
	v_mov_b32_dpp v80, v76 row_mirror row_mask:0xf bank_mask:0xf
	v_mul_f32_e32 v13, v33, v121
	v_mul_f32_e32 v17, v33, v142
	v_mul_f32_e32 v13, v21, v13
	v_mul_f32_e32 v21, v1, v17
	v_mul_f32_e32 v1, v33, v140
	s_waitcnt lgkmcnt(0)
	v_add_f32_e32 v76, v76, v80
	v_add_f32_e32 v77, v77, v81
	v_mul_f32_e32 v109, v9, v1
	v_mul_f32_e32 v1, v33, v124
	v_fma_f32 v76, v76, s46, v78
	v_fma_f32 v77, v77, s46, v78
	v_mul_f32_e32 v17, v25, v1
	v_mul_f32_e32 v9, 0x4b800000, v77
	v_cmp_gt_f32_e32 vcc, s60, v77
	v_mul_f32_e32 v25, 0x4b800000, v76
	v_cmp_gt_f32_e64 s[0:1], s60, v76
	v_cndmask_b32_e32 v9, v77, v9, vcc
	v_mul_f32_e32 v1, v33, v120
	v_cndmask_b32_e64 v25, v76, v25, s[0:1]
	v_mul_f32_e32 v76, v126, v142
	v_mul_f32_e32 v77, v126, v143
	v_mul_f32_e32 v32, v48, v76
	v_mul_f32_e32 v33, v49, v77
	s_waitcnt vmcnt(7)
	v_mov_b32_e32 v76, v85
	s_waitcnt vmcnt(6)
	v_mov_b32_e32 v77, v84
	v_rsq_f32_e32 v9, v9
	v_mul_f32_e32 v48, v32, v84
	v_mul_f32_e32 v49, v33, v85
	v_mul_f32_e32 v32, v32, v76
	v_mul_f32_e32 v33, v33, v77
	v_mul_f32_e32 v76, v126, v140
	v_mul_f32_e32 v77, v126, v141
	v_rsq_f32_e32 v25, v25
	v_mul_f32_e32 v36, v52, v76
	v_mul_f32_e32 v37, v53, v77
	s_waitcnt vmcnt(5)
	v_mov_b32_e32 v76, v97
	s_waitcnt vmcnt(4)
	v_mov_b32_e32 v77, v96
	v_mul_f32_e32 v52, v36, v96
	v_mul_f32_e32 v53, v37, v97
	v_mul_f32_e32 v36, v36, v76
	v_mul_f32_e32 v37, v37, v77
	v_mul_f32_e32 v76, v126, v124
	v_mul_f32_e32 v77, v126, v125
	v_mul_f32_e32 v56, v56, v76
	v_mul_f32_e32 v57, v57, v77
	s_waitcnt vmcnt(3)
	v_mov_b32_e32 v78, v101
	s_waitcnt vmcnt(2)
	v_mov_b32_e32 v79, v100
	v_mul_f32_e32 v110, v29, v1
	v_mul_f32_e32 v1, 0x45800000, v9
	v_mul_f32_e32 v76, v56, v100
	v_mul_f32_e32 v77, v57, v101
	v_mul_f32_e32 v56, v56, v78
	v_mul_f32_e32 v57, v57, v79
	v_mul_f32_e32 v78, v126, v120
	v_mul_f32_e32 v79, v126, v121
	v_mov_b32_e32 v61, v44
	v_cndmask_b32_e32 v148, v9, v1, vcc
	v_mul_f32_e32 v1, 0x45800000, v25
	v_mul_f32_e32 v60, v60, v78
	v_mul_f32_e32 v61, v61, v79
	v_cndmask_b32_e64 v146, v25, v1, s[0:1]
	s_waitcnt vmcnt(0)
	v_mul_f32_e32 v78, v60, v102
	v_mul_f32_e32 v79, v61, v103
	v_mov_b32_e32 v80, v103
	v_mov_b32_e32 v81, v102
	v_cndmask_b32_e64 v64, v202, 1.0, s[56:57]
	v_mul_f32_e32 v60, v60, v80
	v_mul_f32_e32 v61, v61, v81
	s_waitcnt vmcnt(8)
	v_mov_b32_e32 v1, v161
	v_mov_b32_e32 v9, v162
	v_mov_b32_e32 v25, v185
	v_mov_b32_e32 v29, v186
	v_mov_b32_e32 v40, v187
	v_mov_b32_e32 v44, v207
	v_mov_b32_e32 v89, v212
	v_mov_b32_e32 v93, v213
	global_load_dword v161, v144, s[6:7] offset:768
	global_load_dword v162, v144, s[8:9] offset:768
	global_load_dword v185, v144, s[6:7] offset:832
	global_load_dword v186, v144, s[8:9] offset:832
	global_load_dword v187, v144, s[6:7] offset:896
	global_load_dword v207, v144, s[8:9] offset:896
	global_load_dword v212, v144, s[6:7] offset:960
	global_load_dword v213, v144, s[8:9] offset:960
	v_mov_b32_e32 v82, v33
	v_mov_b32_e32 v84, v37
	v_mov_b32_e32 v80, v49
	v_mov_b32_e32 v86, v53
	v_mov_b32_e32 v90, v77
	v_mov_b32_e32 v94, v57
	v_mov_b32_e32 v96, v79
	v_mov_b32_e32 v98, v61
	v_mul_f32_e32 v33, v204, v1
	v_mul_f32_e32 v83, v127, v9
	v_mul_f32_e32 v81, v127, v1
	v_mul_f32_e32 v49, v204, v9
	v_add_f32_e32 v32, v32, v82
	v_add_f32_e32 v33, v33, v83
	v_add_f32_e64 v48, v80, -v48
	v_add_f32_e64 v49, v81, -v49
	v_mul_f32_e32 v37, v104, v25
	v_mul_f32_e32 v85, v150, v29
	v_mul_f32_e32 v87, v150, v25
	v_mul_f32_e32 v53, v104, v29
	v_mul_f32_e32 v91, v151, v40
	v_mul_f32_e32 v77, v105, v44
	v_mul_f32_e32 v95, v151, v44
	v_mul_f32_e32 v57, v105, v40
	v_mul_f32_e32 v97, v203, v89
	v_mul_f32_e32 v79, v106, v93
	v_mul_f32_e32 v99, v203, v93
	v_mul_f32_e32 v61, v106, v89
	v_add_f32_e32 v36, v36, v84
	v_add_f32_e32 v37, v37, v85
	v_add_f32_e32 v56, v56, v94
	v_add_f32_e32 v57, v57, v95
	v_add_f32_e32 v60, v60, v98
	v_add_f32_e32 v61, v61, v99
	v_mul_f32_e32 v84, v64, v32
	v_mul_f32_e32 v85, v64, v33
	v_add_f32_e64 v32, v86, -v52
	v_add_f32_e64 v33, v87, -v53
	v_mul_f32_e32 v86, v64, v36
	v_mul_f32_e32 v87, v64, v37
	v_add_f32_e64 v36, v90, -v76
	v_add_f32_e64 v37, v91, -v77
	v_add_f32_e64 v52, v96, -v78
	v_add_f32_e64 v53, v97, -v79
	v_mul_f32_e32 v90, v64, v56
	v_mul_f32_e32 v91, v64, v57
	v_mul_f32_e32 v76, v64, v48
	v_mul_f32_e32 v77, v64, v49
	v_mul_f32_e32 v78, v64, v32
	v_mul_f32_e32 v79, v64, v33
	v_mul_f32_e32 v80, v64, v36
	v_mul_f32_e32 v81, v64, v37
	v_mul_f32_e32 v82, v64, v52
	v_mul_f32_e32 v83, v64, v53
	v_mul_f32_e32 v94, v64, v60
	v_mul_f32_e32 v95, v64, v61
	s_waitcnt vmcnt(8)
	v_mov_b32_e32 v37, v66
	s_nop 0
	v_mov_b32_e32 v36, v67
	s_nop 0
	v_mov_b32_e32 v33, v68
	v_mov_b32_e32 v32, v69
	s_nop 0
	v_mov_b32_e32 v49, v71
	v_mov_b32_e32 v48, v74
	v_mov_b32_e32 v57, v75
	s_nop 0
	v_mov_b32_e32 v56, v160
	global_load_dword v66, v144, s[10:11]
	global_load_dword v67, v144, s[12:13]
	global_load_dword v68, v144, s[10:11] offset:64
	global_load_dword v69, v144, s[12:13] offset:64
	global_load_dword v71, v144, s[10:11] offset:128
	global_load_dword v74, v144, s[12:13] offset:128
	global_load_dword v75, v144, s[10:11] offset:192
	global_load_dword v160, v144, s[12:13] offset:192
	v_mul_f32_e32 v52, v92, v142
	v_mul_f32_e32 v53, v92, v143
	v_mov_b32_e32 v60, v50
	v_mov_b32_e32 v61, v34
	v_mul_f32_e32 v96, v92, v140
	v_mul_f32_e32 v97, v92, v141
	v_mov_b32_e32 v98, v54
	v_mov_b32_e32 v99, v38
	v_mul_f32_e32 v100, v92, v124
	v_mul_f32_e32 v101, v92, v125
	v_mov_b32_e32 v102, v58
	v_mov_b32_e32 v103, v42
	v_mul_f32_e32 v93, v92, v121
	v_mul_f32_e32 v92, v92, v120
	v_mov_b32_e32 v104, v62
	v_mov_b32_e32 v105, v46
	v_mul_f32_e32 v52, v60, v52
	v_mul_f32_e32 v53, v61, v53
	v_mul_f32_e32 v60, v98, v96
	v_mul_f32_e32 v61, v99, v97
	v_mul_f32_e32 v96, v102, v100
	v_mul_f32_e32 v97, v103, v101
	v_mul_f32_e32 v92, v104, v92
	v_mul_f32_e32 v93, v105, v93
	v_mov_b32_e32 v100, v37
	v_mul_f32_e32 v98, v52, v36
	v_mul_f32_e32 v99, v53, v37
	v_mov_b32_e32 v101, v36
	v_mul_f32_e32 v102, v60, v32
	v_mul_f32_e32 v103, v61, v33
	v_mov_b32_e32 v36, v33
	v_mov_b32_e32 v37, v32
	v_mul_f32_e32 v104, v96, v48
	v_mul_f32_e32 v105, v97, v49
	v_mov_b32_e32 v32, v49
	v_mov_b32_e32 v33, v48
	v_mov_b32_e32 v106, v57
	v_mov_b32_e32 v107, v56
	v_mul_f32_e32 v106, v92, v106
	v_mul_f32_e32 v107, v93, v107
	v_mul_f32_e32 v48, v92, v56
	v_mul_f32_e32 v49, v93, v57
	v_mul_f32_e32 v52, v52, v100
	v_mul_f32_e32 v53, v53, v101
	v_mul_f32_e32 v56, v60, v36
	v_mul_f32_e32 v57, v61, v37
	v_mul_f32_e32 v60, v96, v32
	v_mul_f32_e32 v61, v97, v33
	s_waitcnt vmcnt(8)
	v_mov_b32_e32 v114, v161
	v_mov_b32_e32 v115, v162
	s_nop 0
	v_mov_b32_e32 v96, v185
	s_nop 0
	v_mov_b32_e32 v97, v186
	s_nop 0
	v_mov_b32_e32 v92, v187
	v_mov_b32_e32 v93, v207
	v_mov_b32_e32 v112, v212
	v_mov_b32_e32 v113, v213
	global_load_dword v161, v144, s[10:11] offset:256
	global_load_dword v162, v144, s[12:13] offset:256
	global_load_dword v185, v144, s[10:11] offset:320
	global_load_dword v186, v144, s[12:13] offset:320
	global_load_dword v187, v144, s[10:11] offset:384
	global_load_dword v207, v144, s[12:13] offset:384
	global_load_dword v212, v144, s[10:11] offset:448
	global_load_dword v213, v144, s[12:13] offset:448
	v_mov_b32_e32 v32, v143
	v_mov_b32_e32 v33, v142
	v_mov_b32_e32 v50, v35
	v_mov_b32_e32 v34, v141
	v_mov_b32_e32 v35, v140
	v_mov_b32_e32 v54, v39
	v_mov_b32_e32 v36, v125
	v_mov_b32_e32 v37, v124
	v_mov_b32_e32 v38, v121
	v_mov_b32_e32 v39, v120
	v_mul_f32_e32 v116, v88, v32
	v_mul_f32_e32 v117, v88, v33
	v_mov_b32_e32 v58, v43
	v_mov_b32_e32 v62, v47
	v_mul_f32_e32 v118, v88, v34
	v_mul_f32_e32 v119, v88, v35
	v_mul_f32_e32 v122, v88, v36
	v_mul_f32_e32 v123, v88, v37
	v_mul_f32_e32 v89, v88, v39
	v_mul_f32_e32 v88, v88, v38
	v_mul_f32_e32 v50, v50, v116
	v_mul_f32_e32 v51, v51, v117
	v_mul_f32_e32 v54, v54, v118
	v_mul_f32_e32 v55, v55, v119
	v_mul_f32_e32 v58, v58, v122
	v_mul_f32_e32 v59, v59, v123
	v_mul_f32_e32 v62, v62, v88
	v_mul_f32_e32 v63, v63, v89
	v_mov_b32_e32 v42, v52
	v_mov_b32_e32 v100, v60
	v_mov_b32_e32 v46, v56
	v_mov_b32_e32 v117, v114
	v_mov_b32_e32 v116, v115
	v_mul_f32_e32 v88, v50, v114
	v_mul_f32_e32 v89, v51, v115
	v_mul_f32_e32 v50, v50, v116
	v_mul_f32_e32 v51, v51, v117
	v_mov_b32_e32 v123, v92
	v_mov_b32_e32 v122, v93
	v_mul_f32_e32 v114, v54, v96
	v_mul_f32_e32 v115, v55, v97
	v_mov_b32_e32 v118, v97
	v_mov_b32_e32 v119, v96
	v_mul_f32_e32 v96, v58, v92
	v_mul_f32_e32 v97, v59, v93
	v_mul_f32_e32 v58, v58, v122
	v_mul_f32_e32 v59, v59, v123
	v_mov_b32_e32 v43, v51
	v_pk_mov_b32 v[50:51], v[52:53], v[50:51] op_sel:[1,0]
	v_mul_f32_e32 v54, v54, v118
	v_mul_f32_e32 v55, v55, v119
	v_mov_b32_e32 v101, v59
	v_pk_mov_b32 v[58:59], v[60:61], v[58:59] op_sel:[1,0]
	v_add_f32_e32 v42, v42, v50
	v_add_f32_e32 v43, v43, v51
	v_mov_b32_e32 v47, v55
	v_pk_mov_b32 v[54:55], v[56:57], v[54:55] op_sel:[1,0]
	v_add_f32_e32 v50, v100, v58
	v_add_f32_e32 v51, v101, v59
	v_mul_f32_e32 v100, v64, v42
	v_mul_f32_e32 v101, v64, v43
	v_mov_b32_e32 v42, v113
	v_mov_b32_e32 v43, v112
	v_mul_f32_e32 v92, v62, v112
	v_mul_f32_e32 v93, v63, v113
	v_pk_mov_b32 v[126:127], v[98:99], v[88:89] op_sel:[1,0]
	v_mov_b32_e32 v99, v89
	v_pk_mov_b32 v[88:89], v[102:103], v[114:115] op_sel:[1,0]
	v_mov_b32_e32 v103, v115
	v_add_f32_e32 v46, v46, v54
	v_add_f32_e32 v47, v47, v55
	v_mul_f32_e32 v42, v62, v42
	v_mul_f32_e32 v43, v63, v43
	v_pk_mov_b32 v[114:115], v[104:105], v[96:97] op_sel:[1,0]
	v_mov_b32_e32 v105, v97
	v_pk_mov_b32 v[96:97], v[48:49], v[92:93] op_sel:[1,0]
	v_mov_b32_e32 v49, v93
	v_add_f32_e64 v52, v88, -v102
	v_add_f32_e64 v53, v89, -v103
	v_mul_f32_e32 v102, v64, v46
	v_mul_f32_e32 v103, v64, v47
	v_mov_b32_e32 v46, v106
	v_mov_b32_e32 v47, v43
	v_pk_mov_b32 v[42:43], v[106:107], v[42:43] op_sel:[1,0]
	v_add_f32_e64 v92, v126, -v98
	v_add_f32_e64 v93, v127, -v99
	v_add_f32_e64 v56, v114, -v104
	v_add_f32_e64 v57, v115, -v105
	v_add_f32_e64 v48, v96, -v48
	v_add_f32_e64 v49, v97, -v49
	v_add_f32_e32 v42, v46, v42
	v_add_f32_e32 v43, v47, v43
	v_mul_f32_e32 v88, v64, v92
	v_mul_f32_e32 v89, v64, v93
	v_mul_f32_e32 v92, v64, v52
	v_mul_f32_e32 v93, v64, v53
	v_mul_f32_e32 v96, v64, v56
	v_mul_f32_e32 v97, v64, v57
	v_mul_f32_e32 v104, v64, v50
	v_mul_f32_e32 v105, v64, v51
	v_mul_f32_e32 v98, v64, v48
	v_mul_f32_e32 v99, v64, v49
	v_mul_f32_e32 v106, v64, v42
	v_mul_f32_e32 v107, v64, v43
	s_waitcnt vmcnt(8)
	v_mov_b32_e32 v47, v66
	s_nop 0
	v_mov_b32_e32 v46, v67
	s_nop 0
	v_mov_b32_e32 v43, v68
	v_mov_b32_e32 v42, v69
	s_nop 0
	v_mov_b32_e32 v49, v71
	v_mov_b32_e32 v48, v74
	v_mov_b32_e32 v53, v75
	s_nop 0
	v_mov_b32_e32 v52, v160
	global_load_dword v66, v144, s[10:11] offset:512
	global_load_dword v67, v144, s[12:13] offset:512
	global_load_dword v68, v144, s[10:11] offset:576
	global_load_dword v69, v144, s[12:13] offset:576
	global_load_dword v71, v144, s[10:11] offset:640
	global_load_dword v74, v144, s[12:13] offset:640
	global_load_dword v75, v144, s[10:11] offset:704
	global_load_dword v160, v144, s[12:13] offset:704
	v_mul_f32_e32 v50, v108, v142
	v_mul_f32_e32 v51, v108, v143
	v_mov_b32_e32 v1, v4
	v_mul_f32_e32 v54, v108, v140
	v_mul_f32_e32 v55, v108, v141
	v_mov_b32_e32 v9, v12
	v_mul_f32_e32 v56, v108, v124
	v_mul_f32_e32 v57, v108, v125
	v_mov_b32_e32 v25, v16
	v_mul_f32_e32 v58, v108, v120
	v_mul_f32_e32 v59, v108, v121
	v_mov_b32_e32 v29, v20
	v_mul_f32_e32 v0, v0, v50
	v_mul_f32_e32 v1, v1, v51
	v_mul_f32_e32 v8, v8, v54
	v_mul_f32_e32 v9, v9, v55
	v_mul_f32_e32 v24, v24, v56
	v_mul_f32_e32 v25, v25, v57
	v_mul_f32_e32 v28, v28, v58
	v_mul_f32_e32 v29, v29, v59
	v_mov_b32_e32 v54, v47
	v_mov_b32_e32 v55, v46
	v_mov_b32_e32 v56, v43
	v_mov_b32_e32 v57, v42
	v_mov_b32_e32 v58, v49
	v_mov_b32_e32 v59, v48
	v_mul_f32_e32 v50, v0, v46
	v_mul_f32_e32 v51, v1, v47
	v_mul_f32_e32 v46, v8, v42
	v_mul_f32_e32 v47, v9, v43
	v_mul_f32_e32 v42, v24, v48
	v_mul_f32_e32 v43, v25, v49
	v_mov_b32_e32 v60, v53
	v_mov_b32_e32 v61, v52
	v_mul_f32_e32 v48, v28, v52
	v_mul_f32_e32 v49, v29, v53
	v_mul_f32_e32 v0, v0, v54
	v_mul_f32_e32 v1, v1, v55
	v_mul_f32_e32 v8, v8, v56
	v_mul_f32_e32 v9, v9, v57
	v_mul_f32_e32 v24, v24, v58
	v_mul_f32_e32 v25, v25, v59
	v_mul_f32_e32 v28, v28, v60
	v_mul_f32_e32 v29, v29, v61
	s_waitcnt vmcnt(8)
	v_mov_b32_e32 v60, v161
	v_mov_b32_e32 v61, v162
	v_mov_b32_e32 v62, v185
	v_mov_b32_e32 v63, v186
	s_nop 0
	v_mov_b32_e32 v58, v187
	s_nop 0
	v_mov_b32_e32 v56, v207
	v_mov_b32_e32 v57, v212
	v_mov_b32_e32 v59, v213
	global_load_dword v161, v144, s[10:11] offset:768
	global_load_dword v162, v144, s[12:13] offset:768
	global_load_dword v185, v144, s[10:11] offset:832
	global_load_dword v186, v144, s[12:13] offset:832
	global_load_dword v187, v144, s[10:11] offset:896
	global_load_dword v207, v144, s[12:13] offset:896
	global_load_dword v212, v144, s[10:11] offset:960
	global_load_dword v213, v144, s[12:13] offset:960
	v_mov_b32_e32 v52, v51
	v_mov_b32_e32 v40, v1
	v_mov_b32_e32 v44, v9
	v_mov_b32_e32 v4, v25
	v_mov_b32_e32 v16, v49
	v_mov_b32_e32 v20, v47
	v_mov_b32_e32 v54, v43
	v_mov_b32_e32 v12, v29
	v_mul_f32_e32 v53, v41, v60
	v_mul_f32_e32 v51, v21, v61
	v_mul_f32_e32 v41, v41, v61
	v_mul_f32_e32 v1, v21, v60
	v_add_f32_e32 v0, v0, v40
	v_add_f32_e32 v1, v1, v41
	v_mul_f32_e32 v21, v45, v62
	v_mul_f32_e32 v45, v45, v63
	v_mul_f32_e32 v9, v109, v62
	v_mul_f32_e32 v55, v5, v58
	v_mul_f32_e32 v49, v17, v56
	v_mul_f32_e32 v5, v5, v56
	v_mul_f32_e32 v25, v17, v58
	v_mul_f32_e32 v47, v109, v63
	v_mul_f32_e32 v56, v110, v59
	v_mul_f32_e32 v17, v13, v57
	v_mul_f32_e32 v13, v13, v59
	v_mul_f32_e32 v29, v110, v57
	v_add_f32_e32 v8, v8, v44
	v_add_f32_e32 v9, v9, v45
	v_mov_b32_e32 v43, v49
	v_add_f32_e32 v4, v24, v4
	v_add_f32_e32 v5, v25, v5
	v_mov_b32_e32 v49, v56
	v_add_f32_e32 v12, v28, v12
	v_add_f32_e32 v13, v29, v13
	v_add_f32_e64 v24, v52, -v50
	v_add_f32_e64 v25, v53, -v51
	v_mul_f32_e32 v116, v64, v0
	v_mul_f32_e32 v117, v64, v1
	v_add_f32_e64 v0, v20, -v46
	v_add_f32_e64 v1, v21, -v47
	v_mul_f32_e32 v118, v64, v8
	v_mul_f32_e32 v119, v64, v9
	v_add_f32_e64 v8, v54, -v42
	v_add_f32_e64 v9, v55, -v43
	v_mul_f32_e32 v122, v64, v4
	v_mul_f32_e32 v123, v64, v5
	v_add_f32_e64 v4, v16, -v48
	v_add_f32_e64 v5, v17, -v49
	v_mul_f32_e32 v108, v64, v24
	v_mul_f32_e32 v109, v64, v25
	v_mul_f32_e32 v110, v64, v0
	v_mul_f32_e32 v111, v64, v1
	v_mul_f32_e32 v112, v64, v8
	v_mul_f32_e32 v113, v64, v9
	v_mul_f32_e32 v114, v64, v4
	v_mul_f32_e32 v115, v64, v5
	v_mul_f32_e32 v126, v64, v12
	v_mul_f32_e32 v127, v64, v13
	s_waitcnt vmcnt(8)
	v_mov_b32_e32 v5, v66
	s_nop 0
	v_mov_b32_e32 v4, v67
	s_nop 0
	v_mov_b32_e32 v1, v68
	v_mov_b32_e32 v0, v69
	s_nop 0
	v_mov_b32_e32 v9, v71
	v_mov_b32_e32 v8, v74
	v_mov_b32_e32 v17, v75
	s_nop 0
	v_mov_b32_e32 v16, v160
	v_mul_f32_e32 v12, v148, v142
	v_mul_f32_e32 v13, v148, v143
	v_mov_b32_e32 v20, v2
	v_mov_b32_e32 v21, v6
	v_mul_f32_e32 v24, v148, v140
	v_mul_f32_e32 v25, v148, v141
	v_mov_b32_e32 v28, v10
	v_mov_b32_e32 v29, v14
	v_mul_f32_e32 v40, v148, v124
	v_mul_f32_e32 v41, v148, v125
	v_mov_b32_e32 v42, v26
	v_mov_b32_e32 v43, v18
	v_mul_f32_e32 v44, v148, v120
	v_mul_f32_e32 v45, v148, v121
	v_mov_b32_e32 v46, v30
	v_mov_b32_e32 v47, v22
	v_mul_f32_e32 v12, v20, v12
	v_mul_f32_e32 v13, v21, v13
	v_mul_f32_e32 v20, v28, v24
	v_mul_f32_e32 v21, v29, v25
	v_mul_f32_e32 v24, v42, v40
	v_mul_f32_e32 v25, v43, v41
	v_mul_f32_e32 v28, v46, v44
	v_mul_f32_e32 v29, v47, v45
	v_mov_b32_e32 v42, v5
	v_mov_b32_e32 v43, v4
	v_mov_b32_e32 v44, v1
	v_mov_b32_e32 v45, v0
	v_mov_b32_e32 v46, v9
	v_mov_b32_e32 v47, v8
	v_mul_f32_e32 v40, v12, v4
	v_mul_f32_e32 v41, v13, v5
	v_mul_f32_e32 v4, v20, v0
	v_mul_f32_e32 v5, v21, v1
	v_mul_f32_e32 v0, v24, v8
	v_mul_f32_e32 v1, v25, v9
	v_mov_b32_e32 v48, v17
	v_mov_b32_e32 v49, v16
	v_mul_f32_e32 v8, v28, v16
	v_mul_f32_e32 v9, v29, v17
	v_mul_f32_e32 v12, v12, v42
	v_mul_f32_e32 v13, v13, v43
	v_mul_f32_e32 v16, v20, v44
	v_mul_f32_e32 v17, v21, v45
	v_mul_f32_e32 v20, v24, v46
	v_mul_f32_e32 v21, v25, v47
	v_mul_f32_e32 v24, v28, v48
	v_mul_f32_e32 v25, v29, v49
	v_or_b32_e32 v48, 0x1380, v144
	v_mov_b32_e32 v49, v145
	v_lshl_add_u64 v[50:51], s[6:7], 0, v[48:49]
	s_waitcnt vmcnt(0)
	v_mov_b32_e32 v42, v161
	s_nop 0
	v_mov_b32_e32 v43, v162
	s_nop 0
	v_mov_b32_e32 v28, v185
	v_mov_b32_e32 v29, v186
	s_nop 0
	v_mov_b32_e32 v44, v187
	v_mov_b32_e32 v45, v207
	v_mov_b32_e32 v46, v212
	s_nop 0
	v_mov_b32_e32 v47, v213
	ds_read_b32 v66, v129 offset:45056
	ds_read_b32 v67, v129 offset:45060
	ds_read_b32 v68, v129 offset:45064
	ds_read_b32 v69, v129 offset:45068
	ds_read_b32 v71, v129 offset:49152
	ds_read_b32 v74, v129 offset:49156
	ds_read_b32 v75, v129 offset:49160
	ds_read_b32 v160, v129 offset:49164
	ds_read_b32 v161, v129 offset:53248
	ds_read_b32 v162, v129 offset:53252
	ds_read_b32 v185, v129 offset:53256
	ds_read_b32 v186, v129 offset:53260
	ds_read_b32 v187, v129 offset:57344
	ds_read_b32 v207, v129 offset:57348
	ds_read_b32 v212, v129 offset:57352
	ds_read_b32 v213, v129 offset:57356
	s_waitcnt lgkmcnt(0)
	v_mul_f32_e32 v32, v32, v146
	v_mul_f32_e32 v33, v33, v146
	v_mov_b32_e32 v2, v7
	v_mul_f32_e32 v34, v34, v146
	v_mul_f32_e32 v35, v35, v146
	v_mov_b32_e32 v10, v15
	v_mul_f32_e32 v36, v36, v146
	v_mul_f32_e32 v37, v37, v146
	v_mov_b32_e32 v26, v19
	v_mul_f32_e32 v38, v38, v146
	v_mul_f32_e32 v39, v39, v146
	v_mov_b32_e32 v30, v23
	v_mul_f32_e32 v2, v2, v32
	v_mul_f32_e32 v3, v3, v33
	v_mul_f32_e32 v10, v10, v34
	v_mul_f32_e32 v11, v11, v35
	v_mul_f32_e32 v26, v26, v36
	v_mul_f32_e32 v27, v27, v37
	v_mul_f32_e32 v30, v30, v38
	v_mul_f32_e32 v31, v31, v39
	v_mov_b32_e32 v6, v12
	v_mov_b32_e32 v14, v16
	v_mov_b32_e32 v18, v20
	v_mov_b32_e32 v22, v24
	v_mov_b32_e32 v35, v42
	v_mul_f32_e32 v32, v2, v42
	v_mul_f32_e32 v33, v3, v43
	v_mov_b32_e32 v34, v43
	v_mul_f32_e32 v36, v10, v28
	v_mul_f32_e32 v37, v11, v29
	v_mov_b32_e32 v38, v29
	v_mov_b32_e32 v39, v28
	v_mul_f32_e32 v28, v26, v44
	v_mul_f32_e32 v29, v27, v45
	v_mov_b32_e32 v42, v45
	v_mov_b32_e32 v43, v44
	v_mov_b32_e32 v48, v47
	v_mov_b32_e32 v49, v46
	v_mul_f32_e32 v44, v30, v46
	v_mul_f32_e32 v45, v31, v47
	v_pk_mov_b32 v[46:47], v[40:41], v[32:33] op_sel:[1,0]
	v_mov_b32_e32 v41, v33
	v_mul_f32_e32 v2, v2, v34
	v_mul_f32_e32 v3, v3, v35
	v_pk_mov_b32 v[32:33], v[4:5], v[36:37] op_sel:[1,0]
	v_mov_b32_e32 v5, v37
	v_mul_f32_e32 v10, v10, v38
	v_mul_f32_e32 v11, v11, v39
	v_pk_mov_b32 v[34:35], v[0:1], v[28:29] op_sel:[1,0]
	v_mov_b32_e32 v1, v29
	v_mul_f32_e32 v26, v26, v42
	v_mul_f32_e32 v27, v27, v43
	v_mul_f32_e32 v30, v30, v48
	v_mul_f32_e32 v31, v31, v49
	v_pk_mov_b32 v[28:29], v[8:9], v[44:45] op_sel:[1,0]
	v_mov_b32_e32 v9, v45
	v_mov_b32_e32 v7, v3
	v_pk_mov_b32 v[2:3], v[12:13], v[2:3] op_sel:[1,0]
	v_add_f32_e64 v4, v32, -v4
	v_add_f32_e64 v5, v33, -v5
	v_mov_b32_e32 v15, v11
	v_pk_mov_b32 v[10:11], v[16:17], v[10:11] op_sel:[1,0]
	v_add_f32_e64 v0, v34, -v0
	v_add_f32_e64 v1, v35, -v1
	v_mov_b32_e32 v19, v27
	v_pk_mov_b32 v[12:13], v[20:21], v[26:27] op_sel:[1,0]
	v_mov_b32_e32 v23, v31
	v_pk_mov_b32 v[16:17], v[24:25], v[30:31] op_sel:[1,0]
	v_add_f32_e64 v36, v46, -v40
	v_add_f32_e64 v37, v47, -v41
	v_add_f32_e64 v8, v28, -v8
	v_add_f32_e64 v9, v29, -v9
	v_add_f32_e32 v2, v6, v2
	v_add_f32_e32 v3, v7, v3
	v_mul_f32_e32 v124, v64, v4
	v_mul_f32_e32 v125, v64, v5
	v_add_f32_e32 v4, v14, v10
	v_add_f32_e32 v5, v15, v11
	v_mul_f32_e32 v140, v64, v0
	v_mul_f32_e32 v141, v64, v1
	v_add_f32_e32 v0, v18, v12
	v_add_f32_e32 v1, v19, v13
	v_add_f32_e32 v6, v22, v16
	v_add_f32_e32 v7, v23, v17
	v_mul_f32_e32 v120, v64, v36
	v_mul_f32_e32 v121, v64, v37
	v_mul_f32_e32 v142, v64, v8
	v_mul_f32_e32 v143, v64, v9
	v_mul_f32_e32 v144, v64, v2
	v_mul_f32_e32 v145, v64, v3
	v_mul_f32_e32 v146, v64, v4
	v_mul_f32_e32 v147, v64, v5
	v_mul_f32_e32 v148, v64, v0
	v_mul_f32_e32 v149, v64, v1
	v_mul_f32_e32 v150, v64, v6
	v_mul_f32_e32 v151, v64, v7
	s_branch .Lmy_rp_join
.Lmy_rp_p2:
	s_add_u32 s10, s6, 0x1000
	s_addc_u32 s11, s7, 0
	s_add_u32 s12, s8, 0x1000
	s_addc_u32 s13, s9, 0
	global_load_dword v188, v144, s[6:7] offset:256
	global_load_dword v189, v144, s[8:9] offset:256
	global_load_dword v190, v144, s[6:7] offset:320
	global_load_dword v191, v144, s[8:9] offset:320
	global_load_dword v208, v144, s[6:7] offset:384
	global_load_dword v209, v144, s[8:9] offset:384
	global_load_dword v210, v144, s[6:7] offset:448
	global_load_dword v211, v144, s[8:9] offset:448
	global_load_dword v232, v144, s[6:7] offset:512
	global_load_dword v233, v144, s[8:9] offset:512
	global_load_dword v234, v144, s[6:7] offset:576
	global_load_dword v235, v144, s[8:9] offset:576
	global_load_dword v236, v144, s[6:7] offset:640
	global_load_dword v237, v144, s[8:9] offset:640
	global_load_dword v238, v144, s[6:7] offset:704
	global_load_dword v239, v144, s[8:9] offset:704
	global_load_dword v240, v144, s[6:7] offset:768
	global_load_dword v241, v144, s[8:9] offset:768
	global_load_dword v242, v144, s[6:7] offset:832
	global_load_dword v243, v144, s[8:9] offset:832
	global_load_dword v248, v144, s[6:7] offset:896
	global_load_dword v249, v144, s[8:9] offset:896
	global_load_dword v250, v144, s[6:7] offset:960
	global_load_dword v251, v144, s[8:9] offset:960
	global_load_dword v252, v144, s[10:11]
	global_load_dword v253, v144, s[12:13]
	global_load_dword v254, v144, s[10:11] offset:64
	global_load_dword v255, v144, s[12:13] offset:64
	global_load_dword v66, v144, s[10:11] offset:128
	global_load_dword v67, v144, s[12:13] offset:128
	global_load_dword v68, v144, s[10:11] offset:192
	global_load_dword v69, v144, s[12:13] offset:192
	global_load_dword v71, v144, s[10:11] offset:256
	global_load_dword v74, v144, s[12:13] offset:256
	global_load_dword v75, v144, s[10:11] offset:320
	global_load_dword v160, v144, s[12:13] offset:320
	global_load_dword v161, v144, s[10:11] offset:384
	global_load_dword v162, v144, s[12:13] offset:384
	global_load_dword v185, v144, s[10:11] offset:448
	global_load_dword v186, v144, s[12:13] offset:448
	global_load_dword v187, v144, s[10:11] offset:512
	global_load_dword v207, v144, s[12:13] offset:512
	global_load_dword v212, v144, s[10:11] offset:576
	global_load_dword v213, v144, s[12:13] offset:576
	global_load_dword v214, v144, s[10:11] offset:640
	global_load_dword v216, v144, s[12:13] offset:640
	global_load_dword v218, v144, s[10:11] offset:704
	global_load_dword v220, v144, s[12:13] offset:704
	global_load_dword v222, v144, s[10:11] offset:768
	global_load_dword v224, v144, s[12:13] offset:768
	global_load_dword v226, v144, s[10:11] offset:832
	global_load_dword v228, v144, s[12:13] offset:832
	global_load_dword v230, v144, s[10:11] offset:896
	global_load_dword v231, v144, s[12:13] offset:896
	global_load_dword v244, v144, s[10:11] offset:960
	global_load_dword v245, v144, s[12:13] offset:960
	v_lshl_add_u64 v[84:85], s[6:7], 0, v[144:145]
	v_lshl_add_u64 v[94:95], s[8:9], 0, v[144:145]
	global_load_dword v85, v[84:85], off
	s_nop 0
	global_load_dword v84, v[94:95], off
	v_or_b32_e32 v94, 64, v144
	v_mov_b32_e32 v95, v145
	v_lshl_add_u64 v[96:97], s[6:7], 0, v[94:95]
	v_lshl_add_u64 v[94:95], s[8:9], 0, v[94:95]
	global_load_dword v97, v[96:97], off
	s_nop 0
	global_load_dword v96, v[94:95], off
	v_or_b32_e32 v98, 0x80, v144
	v_mov_b32_e32 v99, v145
	v_lshl_add_u64 v[100:101], s[6:7], 0, v[98:99]
	v_lshl_add_u64 v[98:99], s[8:9], 0, v[98:99]
	global_load_dword v101, v[100:101], off
	s_nop 0
	global_load_dword v100, v[98:99], off
	v_or_b32_e32 v98, 0xc0, v144
	v_mov_b32_e32 v99, v145
	v_lshl_add_u64 v[102:103], s[6:7], 0, v[98:99]
	v_lshl_add_u64 v[98:99], s[8:9], 0, v[98:99]
	global_load_dword v103, v[102:103], off
	s_nop 0
	global_load_dword v102, v[98:99], off
	v_mul_f32_e32 v112, v14, v14
	v_mul_f32_e32 v113, v15, v15
	v_mul_f32_e32 v86, v86, v86
	v_mul_f32_e32 v87, v87, v87
	v_fma_f32 v112, v6, v6, v112
	v_fma_f32 v113, v7, v7, v113
	v_mov_b32_e32 v80, v2
	v_mov_b32_e32 v81, v10
	v_mov_b32_e32 v94, v86
	v_mov_b32_e32 v95, v122
	v_mul_f32_e32 v80, v80, v80
	v_mul_f32_e32 v81, v81, v81
	v_add_f32_e32 v94, v113, v94
	v_add_f32_e32 v95, v112, v95
	v_mov_b32_e32 v122, v87
	v_mov_b32_e32 v82, v26
	v_mov_b32_e32 v83, v30
	v_add_f32_e32 v86, v94, v122
	v_add_f32_e32 v87, v95, v123
	v_mov_b32_e32 v94, v90
	v_mov_b32_e32 v95, v80
	v_mul_f32_e32 v82, v82, v82
	v_mul_f32_e32 v83, v83, v83
	v_add_f32_e32 v86, v86, v94
	v_add_f32_e32 v87, v87, v95
	v_mov_b32_e32 v80, v91
	v_add_f32_e32 v80, v86, v80
	v_add_f32_e32 v81, v87, v81
	v_mov_b32_e32 v86, v76
	v_mov_b32_e32 v87, v82
	v_add_f32_e32 v80, v80, v86
	v_add_f32_e32 v81, v81, v87
	v_mov_b32_e32 v82, v77
	v_add_f32_e32 v76, v80, v82
	v_add_f32_e32 v77, v81, v83
	s_nop 1
	v_mov_b32_dpp v81, v77 quad_perm:[1,0,3,2] row_mask:0xf bank_mask:0xf
	v_mov_b32_dpp v80, v76 quad_perm:[1,0,3,2] row_mask:0xf bank_mask:0xf
	v_rsq_f32_e32 v33, v33
	v_mov_b32_e32 v49, v32
	v_mov_b32_e32 v53, v36
	v_mov_b32_e32 v57, v40
	s_waitcnt lgkmcnt(0)
	v_add_f32_e32 v76, v76, v80
	v_add_f32_e32 v77, v77, v81
	s_nop 1
	v_mov_b32_dpp v81, v77 quad_perm:[2,3,0,1] row_mask:0xf bank_mask:0xf
	v_mov_b32_dpp v80, v76 quad_perm:[2,3,0,1] row_mask:0xf bank_mask:0xf
	v_mul_f32_e32 v37, 0x45800000, v33
	v_cndmask_b32_e32 v33, v33, v37, vcc
	v_mul_f32_e32 v37, v33, v143
	v_mul_f32_e32 v41, v5, v37
	s_waitcnt lgkmcnt(0)
	v_add_f32_e32 v76, v76, v80
	v_add_f32_e32 v77, v77, v81
	s_nop 1
	v_mov_b32_dpp v81, v77 row_half_mirror row_mask:0xf bank_mask:0xf
	v_mov_b32_dpp v80, v76 row_half_mirror row_mask:0xf bank_mask:0xf
	v_mul_f32_e32 v5, v33, v141
	v_mul_f32_e32 v45, v13, v5
	v_mul_f32_e32 v5, v33, v125
	v_mul_f32_e32 v5, v17, v5
	s_waitcnt lgkmcnt(0)
	v_add_f32_e32 v76, v76, v80
	v_add_f32_e32 v77, v77, v81
	s_nop 1
	v_mov_b32_dpp v81, v77 row_mirror row_mask:0xf bank_mask:0xf
	v_mov_b32_dpp v80, v76 row_mirror row_mask:0xf bank_mask:0xf
	v_mul_f32_e32 v13, v33, v121
	v_mul_f32_e32 v17, v33, v142
	v_mul_f32_e32 v13, v21, v13
	v_mul_f32_e32 v21, v1, v17
	v_mul_f32_e32 v1, v33, v140
	s_waitcnt lgkmcnt(0)
	v_add_f32_e32 v76, v76, v80
	v_add_f32_e32 v77, v77, v81
	v_mul_f32_e32 v109, v9, v1
	v_mul_f32_e32 v1, v33, v124
	v_fma_f32 v76, v76, s46, v78
	v_fma_f32 v77, v77, s46, v78
	v_mul_f32_e32 v17, v25, v1
	v_mul_f32_e32 v9, 0x4b800000, v77
	v_cmp_gt_f32_e32 vcc, s60, v77
	v_mul_f32_e32 v25, 0x4b800000, v76
	v_cmp_gt_f32_e64 s[0:1], s60, v76
	v_cndmask_b32_e32 v9, v77, v9, vcc
	v_mul_f32_e32 v1, v33, v120
	v_cndmask_b32_e64 v25, v76, v25, s[0:1]
	v_mul_f32_e32 v76, v126, v142
	v_mul_f32_e32 v77, v126, v143
	v_mul_f32_e32 v32, v48, v76
	v_mul_f32_e32 v33, v49, v77
	s_waitcnt vmcnt(7)
	v_mov_b32_e32 v76, v85
	s_waitcnt vmcnt(6)
	v_mov_b32_e32 v77, v84
	v_rsq_f32_e32 v9, v9
	v_mul_f32_e32 v48, v32, v84
	v_mul_f32_e32 v49, v33, v85
	v_mul_f32_e32 v32, v32, v76
	v_mul_f32_e32 v33, v33, v77
	v_mul_f32_e32 v76, v126, v140
	v_mul_f32_e32 v77, v126, v141
	v_rsq_f32_e32 v25, v25
	v_mul_f32_e32 v36, v52, v76
	v_mul_f32_e32 v37, v53, v77
	s_waitcnt vmcnt(5)
	v_mov_b32_e32 v76, v97
	s_waitcnt vmcnt(4)
	v_mov_b32_e32 v77, v96
	v_mul_f32_e32 v52, v36, v96
	v_mul_f32_e32 v53, v37, v97
	v_mul_f32_e32 v36, v36, v76
	v_mul_f32_e32 v37, v37, v77
	v_mul_f32_e32 v76, v126, v124
	v_mul_f32_e32 v77, v126, v125
	v_mul_f32_e32 v56, v56, v76
	v_mul_f32_e32 v57, v57, v77
	s_waitcnt vmcnt(3)
	v_mov_b32_e32 v78, v101
	s_waitcnt vmcnt(2)
	v_mov_b32_e32 v79, v100
	v_mul_f32_e32 v110, v29, v1
	v_mul_f32_e32 v1, 0x45800000, v9
	v_mul_f32_e32 v76, v56, v100
	v_mul_f32_e32 v77, v57, v101
	v_mul_f32_e32 v56, v56, v78
	v_mul_f32_e32 v57, v57, v79
	v_mul_f32_e32 v78, v126, v120
	v_mul_f32_e32 v79, v126, v121
	v_mov_b32_e32 v61, v44
	v_cndmask_b32_e32 v148, v9, v1, vcc
	v_mul_f32_e32 v1, 0x45800000, v25
	v_mul_f32_e32 v60, v60, v78
	v_mul_f32_e32 v61, v61, v79
	v_cndmask_b32_e64 v146, v25, v1, s[0:1]
	s_waitcnt vmcnt(0)
	v_mul_f32_e32 v78, v60, v102
	v_mul_f32_e32 v79, v61, v103
	v_mov_b32_e32 v80, v103
	v_mov_b32_e32 v81, v102
	v_cndmask_b32_e64 v64, v202, 1.0, s[56:57]
	v_mul_f32_e32 v60, v60, v80
	v_mul_f32_e32 v61, v61, v81
	s_waitcnt vmcnt(0)
	v_mov_b32_e32 v1, v188
	v_mov_b32_e32 v9, v189
	v_mov_b32_e32 v25, v190
	v_mov_b32_e32 v29, v191
	v_mov_b32_e32 v40, v208
	v_mov_b32_e32 v44, v209
	v_mov_b32_e32 v89, v210
	v_mov_b32_e32 v93, v211
	v_mov_b32_e32 v82, v33
	v_mov_b32_e32 v84, v37
	v_mov_b32_e32 v80, v49
	v_mov_b32_e32 v86, v53
	v_mov_b32_e32 v90, v77
	v_mov_b32_e32 v94, v57
	v_mov_b32_e32 v96, v79
	v_mov_b32_e32 v98, v61
	s_waitcnt vmcnt(7)
	v_mul_f32_e32 v33, v204, v1
	s_waitcnt vmcnt(6)
	v_mul_f32_e32 v83, v127, v9
	v_mul_f32_e32 v81, v127, v1
	v_mul_f32_e32 v49, v204, v9
	v_add_f32_e32 v32, v32, v82
	v_add_f32_e32 v33, v33, v83
	v_add_f32_e64 v48, v80, -v48
	v_add_f32_e64 v49, v81, -v49
	s_waitcnt vmcnt(5)
	v_mul_f32_e32 v37, v104, v25
	s_waitcnt vmcnt(4)
	v_mul_f32_e32 v85, v150, v29
	v_mul_f32_e32 v87, v150, v25
	v_mul_f32_e32 v53, v104, v29
	s_waitcnt vmcnt(3)
	v_mul_f32_e32 v91, v151, v40
	s_waitcnt vmcnt(2)
	v_mul_f32_e32 v77, v105, v44
	v_mul_f32_e32 v95, v151, v44
	v_mul_f32_e32 v57, v105, v40
	s_waitcnt vmcnt(1)
	v_mul_f32_e32 v97, v203, v89
	s_waitcnt vmcnt(0)
	v_mul_f32_e32 v79, v106, v93
	v_mul_f32_e32 v99, v203, v93
	v_mul_f32_e32 v61, v106, v89
	v_add_f32_e32 v36, v36, v84
	v_add_f32_e32 v37, v37, v85
	v_add_f32_e32 v56, v56, v94
	v_add_f32_e32 v57, v57, v95
	v_add_f32_e32 v60, v60, v98
	v_add_f32_e32 v61, v61, v99
	v_mul_f32_e32 v84, v64, v32
	v_mul_f32_e32 v85, v64, v33
	v_add_f32_e64 v32, v86, -v52
	v_add_f32_e64 v33, v87, -v53
	v_mul_f32_e32 v86, v64, v36
	v_mul_f32_e32 v87, v64, v37
	v_add_f32_e64 v36, v90, -v76
	v_add_f32_e64 v37, v91, -v77
	v_add_f32_e64 v52, v96, -v78
	v_add_f32_e64 v53, v97, -v79
	v_mul_f32_e32 v90, v64, v56
	v_mul_f32_e32 v91, v64, v57
	v_mul_f32_e32 v76, v64, v48
	v_mul_f32_e32 v77, v64, v49
	v_mul_f32_e32 v78, v64, v32
	v_mul_f32_e32 v79, v64, v33
	v_mul_f32_e32 v80, v64, v36
	v_mul_f32_e32 v81, v64, v37
	v_mul_f32_e32 v82, v64, v52
	v_mul_f32_e32 v83, v64, v53
	v_mul_f32_e32 v94, v64, v60
	v_mul_f32_e32 v95, v64, v61
	s_waitcnt vmcnt(0)
	v_mov_b32_e32 v37, v232
	s_nop 0
	v_mov_b32_e32 v36, v233
	s_nop 0
	v_mov_b32_e32 v33, v234
	v_mov_b32_e32 v32, v235
	s_nop 0
	v_mov_b32_e32 v49, v236
	v_mov_b32_e32 v48, v237
	v_mov_b32_e32 v57, v238
	s_nop 0
	v_mov_b32_e32 v56, v239
	v_mul_f32_e32 v52, v92, v142
	v_mul_f32_e32 v53, v92, v143
	v_mov_b32_e32 v60, v50
	v_mov_b32_e32 v61, v34
	v_mul_f32_e32 v96, v92, v140
	v_mul_f32_e32 v97, v92, v141
	v_mov_b32_e32 v98, v54
	v_mov_b32_e32 v99, v38
	v_mul_f32_e32 v100, v92, v124
	v_mul_f32_e32 v101, v92, v125
	v_mov_b32_e32 v102, v58
	v_mov_b32_e32 v103, v42
	v_mul_f32_e32 v93, v92, v121
	v_mul_f32_e32 v92, v92, v120
	v_mov_b32_e32 v104, v62
	v_mov_b32_e32 v105, v46
	v_mul_f32_e32 v52, v60, v52
	v_mul_f32_e32 v53, v61, v53
	v_mul_f32_e32 v60, v98, v96
	v_mul_f32_e32 v61, v99, v97
	v_mul_f32_e32 v96, v102, v100
	v_mul_f32_e32 v97, v103, v101
	v_mul_f32_e32 v92, v104, v92
	v_mul_f32_e32 v93, v105, v93
	s_waitcnt vmcnt(7)
	v_mov_b32_e32 v100, v37
	s_waitcnt vmcnt(6)
	v_mul_f32_e32 v98, v52, v36
	v_mul_f32_e32 v99, v53, v37
	v_mov_b32_e32 v101, v36
	s_waitcnt vmcnt(4)
	v_mul_f32_e32 v102, v60, v32
	v_mul_f32_e32 v103, v61, v33
	v_mov_b32_e32 v36, v33
	v_mov_b32_e32 v37, v32
	s_waitcnt vmcnt(2)
	v_mul_f32_e32 v104, v96, v48
	v_mul_f32_e32 v105, v97, v49
	v_mov_b32_e32 v32, v49
	v_mov_b32_e32 v33, v48
	s_waitcnt vmcnt(1)
	v_mov_b32_e32 v106, v57
	s_waitcnt vmcnt(0)
	v_mov_b32_e32 v107, v56
	v_mul_f32_e32 v106, v92, v106
	v_mul_f32_e32 v107, v93, v107
	v_mul_f32_e32 v48, v92, v56
	v_mul_f32_e32 v49, v93, v57
	v_mul_f32_e32 v52, v52, v100
	v_mul_f32_e32 v53, v53, v101
	v_mul_f32_e32 v56, v60, v36
	v_mul_f32_e32 v57, v61, v37
	v_mul_f32_e32 v60, v96, v32
	v_mul_f32_e32 v61, v97, v33
	s_waitcnt vmcnt(0)
	v_mov_b32_e32 v114, v240
	v_mov_b32_e32 v115, v241
	s_nop 0
	v_mov_b32_e32 v96, v242
	s_nop 0
	v_mov_b32_e32 v97, v243
	s_nop 0
	v_mov_b32_e32 v92, v248
	v_mov_b32_e32 v93, v249
	v_mov_b32_e32 v112, v250
	v_mov_b32_e32 v113, v251
	v_mov_b32_e32 v32, v143
	v_mov_b32_e32 v33, v142
	v_mov_b32_e32 v50, v35
	v_mov_b32_e32 v34, v141
	v_mov_b32_e32 v35, v140
	v_mov_b32_e32 v54, v39
	v_mov_b32_e32 v36, v125
	v_mov_b32_e32 v37, v124
	v_mov_b32_e32 v38, v121
	v_mov_b32_e32 v39, v120
	v_mul_f32_e32 v116, v88, v32
	v_mul_f32_e32 v117, v88, v33
	v_mov_b32_e32 v58, v43
	v_mov_b32_e32 v62, v47
	v_mul_f32_e32 v118, v88, v34
	v_mul_f32_e32 v119, v88, v35
	v_mul_f32_e32 v122, v88, v36
	v_mul_f32_e32 v123, v88, v37
	v_mul_f32_e32 v89, v88, v39
	v_mul_f32_e32 v88, v88, v38
	v_mul_f32_e32 v50, v50, v116
	v_mul_f32_e32 v51, v51, v117
	v_mul_f32_e32 v54, v54, v118
	v_mul_f32_e32 v55, v55, v119
	v_mul_f32_e32 v58, v58, v122
	v_mul_f32_e32 v59, v59, v123
	v_mul_f32_e32 v62, v62, v88
	v_mul_f32_e32 v63, v63, v89
	v_mov_b32_e32 v42, v52
	v_mov_b32_e32 v100, v60
	v_mov_b32_e32 v46, v56
	s_waitcnt vmcnt(7)
	v_mov_b32_e32 v117, v114
	s_waitcnt vmcnt(6)
	v_mov_b32_e32 v116, v115
	v_mul_f32_e32 v88, v50, v114
	v_mul_f32_e32 v89, v51, v115
	v_mul_f32_e32 v50, v50, v116
	v_mul_f32_e32 v51, v51, v117
	s_waitcnt vmcnt(3)
	v_mov_b32_e32 v123, v92
	s_waitcnt vmcnt(2)
	v_mov_b32_e32 v122, v93
	v_mul_f32_e32 v114, v54, v96
	v_mul_f32_e32 v115, v55, v97
	v_mov_b32_e32 v118, v97
	v_mov_b32_e32 v119, v96
	v_mul_f32_e32 v96, v58, v92
	v_mul_f32_e32 v97, v59, v93
	v_mul_f32_e32 v58, v58, v122
	v_mul_f32_e32 v59, v59, v123
	v_mov_b32_e32 v43, v51
	v_pk_mov_b32 v[50:51], v[52:53], v[50:51] op_sel:[1,0]
	v_mul_f32_e32 v54, v54, v118
	v_mul_f32_e32 v55, v55, v119
	v_mov_b32_e32 v101, v59
	v_pk_mov_b32 v[58:59], v[60:61], v[58:59] op_sel:[1,0]
	v_add_f32_e32 v42, v42, v50
	v_add_f32_e32 v43, v43, v51
	v_mov_b32_e32 v47, v55
	v_pk_mov_b32 v[54:55], v[56:57], v[54:55] op_sel:[1,0]
	v_add_f32_e32 v50, v100, v58
	v_add_f32_e32 v51, v101, v59
	v_mul_f32_e32 v100, v64, v42
	v_mul_f32_e32 v101, v64, v43
	s_waitcnt vmcnt(0)
	v_mov_b32_e32 v42, v113
	v_mov_b32_e32 v43, v112
	v_mul_f32_e32 v92, v62, v112
	v_mul_f32_e32 v93, v63, v113
	v_pk_mov_b32 v[126:127], v[98:99], v[88:89] op_sel:[1,0]
	v_mov_b32_e32 v99, v89
	v_pk_mov_b32 v[88:89], v[102:103], v[114:115] op_sel:[1,0]
	v_mov_b32_e32 v103, v115
	v_add_f32_e32 v46, v46, v54
	v_add_f32_e32 v47, v47, v55
	v_mul_f32_e32 v42, v62, v42
	v_mul_f32_e32 v43, v63, v43
	v_pk_mov_b32 v[114:115], v[104:105], v[96:97] op_sel:[1,0]
	v_mov_b32_e32 v105, v97
	v_pk_mov_b32 v[96:97], v[48:49], v[92:93] op_sel:[1,0]
	v_mov_b32_e32 v49, v93
	v_add_f32_e64 v52, v88, -v102
	v_add_f32_e64 v53, v89, -v103
	v_mul_f32_e32 v102, v64, v46
	v_mul_f32_e32 v103, v64, v47
	v_mov_b32_e32 v46, v106
	v_mov_b32_e32 v47, v43
	v_pk_mov_b32 v[42:43], v[106:107], v[42:43] op_sel:[1,0]
	v_add_f32_e64 v92, v126, -v98
	v_add_f32_e64 v93, v127, -v99
	v_add_f32_e64 v56, v114, -v104
	v_add_f32_e64 v57, v115, -v105
	v_add_f32_e64 v48, v96, -v48
	v_add_f32_e64 v49, v97, -v49
	v_add_f32_e32 v42, v46, v42
	v_add_f32_e32 v43, v47, v43
	v_mul_f32_e32 v88, v64, v92
	v_mul_f32_e32 v89, v64, v93
	v_mul_f32_e32 v92, v64, v52
	v_mul_f32_e32 v93, v64, v53
	v_mul_f32_e32 v96, v64, v56
	v_mul_f32_e32 v97, v64, v57
	v_mul_f32_e32 v104, v64, v50
	v_mul_f32_e32 v105, v64, v51
	v_mul_f32_e32 v98, v64, v48
	v_mul_f32_e32 v99, v64, v49
	v_mul_f32_e32 v106, v64, v42
	v_mul_f32_e32 v107, v64, v43
	s_waitcnt vmcnt(0)
	v_mov_b32_e32 v47, v252
	s_nop 0
	v_mov_b32_e32 v46, v253
	s_nop 0
	v_mov_b32_e32 v43, v254
	v_mov_b32_e32 v42, v255
	s_nop 0
	v_mov_b32_e32 v49, v66
	v_mov_b32_e32 v48, v67
	v_mov_b32_e32 v53, v68
	s_nop 0
	v_mov_b32_e32 v52, v69
	v_mul_f32_e32 v50, v108, v142
	v_mul_f32_e32 v51, v108, v143
	v_mov_b32_e32 v1, v4
	v_mul_f32_e32 v54, v108, v140
	v_mul_f32_e32 v55, v108, v141
	v_mov_b32_e32 v9, v12
	v_mul_f32_e32 v56, v108, v124
	v_mul_f32_e32 v57, v108, v125
	v_mov_b32_e32 v25, v16
	v_mul_f32_e32 v58, v108, v120
	v_mul_f32_e32 v59, v108, v121
	v_mov_b32_e32 v29, v20
	v_mul_f32_e32 v0, v0, v50
	v_mul_f32_e32 v1, v1, v51
	v_mul_f32_e32 v8, v8, v54
	v_mul_f32_e32 v9, v9, v55
	v_mul_f32_e32 v24, v24, v56
	v_mul_f32_e32 v25, v25, v57
	v_mul_f32_e32 v28, v28, v58
	v_mul_f32_e32 v29, v29, v59
	s_waitcnt vmcnt(7)
	v_mov_b32_e32 v54, v47
	s_waitcnt vmcnt(6)
	v_mov_b32_e32 v55, v46
	s_waitcnt vmcnt(5)
	v_mov_b32_e32 v56, v43
	s_waitcnt vmcnt(4)
	v_mov_b32_e32 v57, v42
	s_waitcnt vmcnt(3)
	v_mov_b32_e32 v58, v49
	s_waitcnt vmcnt(2)
	v_mov_b32_e32 v59, v48
	v_mul_f32_e32 v50, v0, v46
	v_mul_f32_e32 v51, v1, v47
	v_mul_f32_e32 v46, v8, v42
	v_mul_f32_e32 v47, v9, v43
	v_mul_f32_e32 v42, v24, v48
	v_mul_f32_e32 v43, v25, v49
	s_waitcnt vmcnt(1)
	v_mov_b32_e32 v60, v53
	s_waitcnt vmcnt(0)
	v_mov_b32_e32 v61, v52
	v_mul_f32_e32 v48, v28, v52
	v_mul_f32_e32 v49, v29, v53
	v_mul_f32_e32 v0, v0, v54
	v_mul_f32_e32 v1, v1, v55
	v_mul_f32_e32 v8, v8, v56
	v_mul_f32_e32 v9, v9, v57
	v_mul_f32_e32 v24, v24, v58
	v_mul_f32_e32 v25, v25, v59
	v_mul_f32_e32 v28, v28, v60
	v_mul_f32_e32 v29, v29, v61
	s_waitcnt vmcnt(0)
	v_mov_b32_e32 v60, v71
	v_mov_b32_e32 v61, v74
	v_mov_b32_e32 v62, v75
	v_mov_b32_e32 v63, v160
	s_nop 0
	v_mov_b32_e32 v58, v161
	s_nop 0
	v_mov_b32_e32 v56, v162
	v_mov_b32_e32 v57, v185
	v_mov_b32_e32 v59, v186
	v_mov_b32_e32 v52, v51
	v_mov_b32_e32 v40, v1
	v_mov_b32_e32 v44, v9
	v_mov_b32_e32 v4, v25
	v_mov_b32_e32 v16, v49
	v_mov_b32_e32 v20, v47
	v_mov_b32_e32 v54, v43
	v_mov_b32_e32 v12, v29
	s_waitcnt vmcnt(7)
	v_mul_f32_e32 v53, v41, v60
	s_waitcnt vmcnt(6)
	v_mul_f32_e32 v51, v21, v61
	v_mul_f32_e32 v41, v41, v61
	v_mul_f32_e32 v1, v21, v60
	v_add_f32_e32 v0, v0, v40
	v_add_f32_e32 v1, v1, v41
	s_waitcnt vmcnt(5)
	v_mul_f32_e32 v21, v45, v62
	s_waitcnt vmcnt(4)
	v_mul_f32_e32 v45, v45, v63
	v_mul_f32_e32 v9, v109, v62
	s_waitcnt vmcnt(3)
	v_mul_f32_e32 v55, v5, v58
	s_waitcnt vmcnt(2)
	v_mul_f32_e32 v49, v17, v56
	v_mul_f32_e32 v5, v5, v56
	v_mul_f32_e32 v25, v17, v58
	v_mul_f32_e32 v47, v109, v63
	s_waitcnt vmcnt(0)
	v_mul_f32_e32 v56, v110, v59
	v_mul_f32_e32 v17, v13, v57
	v_mul_f32_e32 v13, v13, v59
	v_mul_f32_e32 v29, v110, v57
	v_add_f32_e32 v8, v8, v44
	v_add_f32_e32 v9, v9, v45
	v_mov_b32_e32 v43, v49
	v_add_f32_e32 v4, v24, v4
	v_add_f32_e32 v5, v25, v5
	v_mov_b32_e32 v49, v56
	v_add_f32_e32 v12, v28, v12
	v_add_f32_e32 v13, v29, v13
	v_add_f32_e64 v24, v52, -v50
	v_add_f32_e64 v25, v53, -v51
	v_mul_f32_e32 v116, v64, v0
	v_mul_f32_e32 v117, v64, v1
	v_add_f32_e64 v0, v20, -v46
	v_add_f32_e64 v1, v21, -v47
	v_mul_f32_e32 v118, v64, v8
	v_mul_f32_e32 v119, v64, v9
	v_add_f32_e64 v8, v54, -v42
	v_add_f32_e64 v9, v55, -v43
	v_mul_f32_e32 v122, v64, v4
	v_mul_f32_e32 v123, v64, v5
	v_add_f32_e64 v4, v16, -v48
	v_add_f32_e64 v5, v17, -v49
	v_mul_f32_e32 v108, v64, v24
	v_mul_f32_e32 v109, v64, v25
	v_mul_f32_e32 v110, v64, v0
	v_mul_f32_e32 v111, v64, v1
	v_mul_f32_e32 v112, v64, v8
	v_mul_f32_e32 v113, v64, v9
	v_mul_f32_e32 v114, v64, v4
	v_mul_f32_e32 v115, v64, v5
	v_mul_f32_e32 v126, v64, v12
	v_mul_f32_e32 v127, v64, v13
	s_waitcnt vmcnt(0)
	v_mov_b32_e32 v5, v187
	s_nop 0
	v_mov_b32_e32 v4, v207
	s_nop 0
	v_mov_b32_e32 v1, v212
	v_mov_b32_e32 v0, v213
	s_nop 0
	v_mov_b32_e32 v9, v214
	v_mov_b32_e32 v8, v216
	v_mov_b32_e32 v17, v218
	s_nop 0
	v_mov_b32_e32 v16, v220
	v_mul_f32_e32 v12, v148, v142
	v_mul_f32_e32 v13, v148, v143
	v_mov_b32_e32 v20, v2
	v_mov_b32_e32 v21, v6
	v_mul_f32_e32 v24, v148, v140
	v_mul_f32_e32 v25, v148, v141
	v_mov_b32_e32 v28, v10
	v_mov_b32_e32 v29, v14
	v_mul_f32_e32 v40, v148, v124
	v_mul_f32_e32 v41, v148, v125
	v_mov_b32_e32 v42, v26
	v_mov_b32_e32 v43, v18
	v_mul_f32_e32 v44, v148, v120
	v_mul_f32_e32 v45, v148, v121
	v_mov_b32_e32 v46, v30
	v_mov_b32_e32 v47, v22
	v_mul_f32_e32 v12, v20, v12
	v_mul_f32_e32 v13, v21, v13
	v_mul_f32_e32 v20, v28, v24
	v_mul_f32_e32 v21, v29, v25
	v_mul_f32_e32 v24, v42, v40
	v_mul_f32_e32 v25, v43, v41
	v_mul_f32_e32 v28, v46, v44
	v_mul_f32_e32 v29, v47, v45
	s_waitcnt vmcnt(7)
	v_mov_b32_e32 v42, v5
	s_waitcnt vmcnt(6)
	v_mov_b32_e32 v43, v4
	s_waitcnt vmcnt(5)
	v_mov_b32_e32 v44, v1
	s_waitcnt vmcnt(4)
	v_mov_b32_e32 v45, v0
	s_waitcnt vmcnt(3)
	v_mov_b32_e32 v46, v9
	s_waitcnt vmcnt(2)
	v_mov_b32_e32 v47, v8
	v_mul_f32_e32 v40, v12, v4
	v_mul_f32_e32 v41, v13, v5
	v_mul_f32_e32 v4, v20, v0
	v_mul_f32_e32 v5, v21, v1
	v_mul_f32_e32 v0, v24, v8
	v_mul_f32_e32 v1, v25, v9
	s_waitcnt vmcnt(1)
	v_mov_b32_e32 v48, v17
	s_waitcnt vmcnt(0)
	v_mov_b32_e32 v49, v16
	v_mul_f32_e32 v8, v28, v16
	v_mul_f32_e32 v9, v29, v17
	v_mul_f32_e32 v12, v12, v42
	v_mul_f32_e32 v13, v13, v43
	v_mul_f32_e32 v16, v20, v44
	v_mul_f32_e32 v17, v21, v45
	v_mul_f32_e32 v20, v24, v46
	v_mul_f32_e32 v21, v25, v47
	v_mul_f32_e32 v24, v28, v48
	v_mul_f32_e32 v25, v29, v49
	v_or_b32_e32 v48, 0x1380, v144
	v_mov_b32_e32 v49, v145
	v_lshl_add_u64 v[50:51], s[6:7], 0, v[48:49]
	s_waitcnt vmcnt(0)
	v_mov_b32_e32 v42, v222
	s_nop 0
	v_mov_b32_e32 v43, v224
	s_nop 0
	v_mov_b32_e32 v28, v226
	v_mov_b32_e32 v29, v228
	s_nop 0
	v_mov_b32_e32 v44, v230
	v_mov_b32_e32 v45, v231
	v_mov_b32_e32 v46, v244
	s_nop 0
	v_mov_b32_e32 v47, v245
	v_mul_f32_e32 v32, v32, v146
	v_mul_f32_e32 v33, v33, v146
	v_mov_b32_e32 v2, v7
	v_mul_f32_e32 v34, v34, v146
	v_mul_f32_e32 v35, v35, v146
	v_mov_b32_e32 v10, v15
	v_mul_f32_e32 v36, v36, v146
	v_mul_f32_e32 v37, v37, v146
	v_mov_b32_e32 v26, v19
	v_mul_f32_e32 v38, v38, v146
	v_mul_f32_e32 v39, v39, v146
	v_mov_b32_e32 v30, v23
	v_mul_f32_e32 v2, v2, v32
	v_mul_f32_e32 v3, v3, v33
	v_mul_f32_e32 v10, v10, v34
	v_mul_f32_e32 v11, v11, v35
	v_mul_f32_e32 v26, v26, v36
	v_mul_f32_e32 v27, v27, v37
	v_mul_f32_e32 v30, v30, v38
	v_mul_f32_e32 v31, v31, v39
	v_mov_b32_e32 v6, v12
	v_mov_b32_e32 v14, v16
	v_mov_b32_e32 v18, v20
	v_mov_b32_e32 v22, v24
	s_waitcnt vmcnt(7)
	v_mov_b32_e32 v35, v42
	s_waitcnt vmcnt(6)
	v_mul_f32_e32 v32, v2, v42
	v_mul_f32_e32 v33, v3, v43
	v_mov_b32_e32 v34, v43
	s_waitcnt vmcnt(4)
	v_mul_f32_e32 v36, v10, v28
	v_mul_f32_e32 v37, v11, v29
	v_mov_b32_e32 v38, v29
	v_mov_b32_e32 v39, v28
	s_waitcnt vmcnt(2)
	v_mul_f32_e32 v28, v26, v44
	v_mul_f32_e32 v29, v27, v45
	v_mov_b32_e32 v42, v45
	v_mov_b32_e32 v43, v44
	s_waitcnt vmcnt(0)
	v_mov_b32_e32 v48, v47
	v_mov_b32_e32 v49, v46
	v_mul_f32_e32 v44, v30, v46
	v_mul_f32_e32 v45, v31, v47
	v_pk_mov_b32 v[46:47], v[40:41], v[32:33] op_sel:[1,0]
	v_mov_b32_e32 v41, v33
	v_mul_f32_e32 v2, v2, v34
	v_mul_f32_e32 v3, v3, v35
	v_pk_mov_b32 v[32:33], v[4:5], v[36:37] op_sel:[1,0]
	v_mov_b32_e32 v5, v37
	v_mul_f32_e32 v10, v10, v38
	v_mul_f32_e32 v11, v11, v39
	v_pk_mov_b32 v[34:35], v[0:1], v[28:29] op_sel:[1,0]
	v_mov_b32_e32 v1, v29
	v_mul_f32_e32 v26, v26, v42
	v_mul_f32_e32 v27, v27, v43
	v_mul_f32_e32 v30, v30, v48
	v_mul_f32_e32 v31, v31, v49
	v_pk_mov_b32 v[28:29], v[8:9], v[44:45] op_sel:[1,0]
	v_mov_b32_e32 v9, v45
	v_mov_b32_e32 v7, v3
	v_pk_mov_b32 v[2:3], v[12:13], v[2:3] op_sel:[1,0]
	v_add_f32_e64 v4, v32, -v4
	v_add_f32_e64 v5, v33, -v5
	v_mov_b32_e32 v15, v11
	v_pk_mov_b32 v[10:11], v[16:17], v[10:11] op_sel:[1,0]
	v_add_f32_e64 v0, v34, -v0
	v_add_f32_e64 v1, v35, -v1
	v_mov_b32_e32 v19, v27
	v_pk_mov_b32 v[12:13], v[20:21], v[26:27] op_sel:[1,0]
	v_mov_b32_e32 v23, v31
	v_pk_mov_b32 v[16:17], v[24:25], v[30:31] op_sel:[1,0]
	v_add_f32_e64 v36, v46, -v40
	v_add_f32_e64 v37, v47, -v41
	v_add_f32_e64 v8, v28, -v8
	v_add_f32_e64 v9, v29, -v9
	v_add_f32_e32 v2, v6, v2
	v_add_f32_e32 v3, v7, v3
	v_mul_f32_e32 v124, v64, v4
	v_mul_f32_e32 v125, v64, v5
	v_add_f32_e32 v4, v14, v10
	v_add_f32_e32 v5, v15, v11
	v_mul_f32_e32 v140, v64, v0
	v_mul_f32_e32 v141, v64, v1
	v_add_f32_e32 v0, v18, v12
	v_add_f32_e32 v1, v19, v13
	v_add_f32_e32 v6, v22, v16
	v_add_f32_e32 v7, v23, v17
	v_mul_f32_e32 v120, v64, v36
	v_mul_f32_e32 v121, v64, v37
	v_mul_f32_e32 v142, v64, v8
	v_mul_f32_e32 v143, v64, v9
	v_mul_f32_e32 v144, v64, v2
	v_mul_f32_e32 v145, v64, v3
	v_mul_f32_e32 v146, v64, v4
	v_mul_f32_e32 v147, v64, v5
	v_mul_f32_e32 v148, v64, v0
	v_mul_f32_e32 v149, v64, v1
	v_mul_f32_e32 v150, v64, v6
	v_mul_f32_e32 v151, v64, v7
